# KV up-proj epilogue: the 8 per-row part[r] loads issued up front, one wait (was load, vmcnt(0), scale, 2 stores per row)
# speedup vs baseline: 1.0553x; 1.0095x over previous
; __device__ __forceinline__ u32x4 pack8(const f32x4 a, const f32x4 b) { u32x4 w; w.x = cvt_pk_bf16(a[0], a[1]); w.y = cvt_pk_bf16(a[2], a[3]); w.z = cvt_pk_bf16(b[0], b[1]); w.w = cvt_pk_bf16(b[2], b[3]); return w; }
; #define EPI_ROWLOOP _Pragma("unroll") for (int ai = 0; ai < 2; ++ai) _Pragma("unroll") for (int m = 0; m < 4; ++m)
;     __device__ __forceinline__ void operator()(const f32x4 (&acc)[2][2][4][2], const Unit& u, int wr, int wc, int fr, int fq) const {
;         const int pn = u.pn, row0 = u.pm * BM + wr * 64 + fr, cl = wc * 32 + 8 * fq;
;         bf16_t* base = pn < 4 ? KN : VV;
;         EPI_ROWLOOP { const int r = row0 + ai * HALF + m * 16; const f32x4 pq = part[r]; const float rs = __builtin_amdgcn_rsqf(((pq[0] + pq[1]) + (pq[2] + pq[3])) * (1.0f / 256.0f) + EP_EPS);
;             bf16_t* rowp = base + (size_t)r * 1024 + (pn & 3) * 256 + cl;
; #pragma unroll
;             for (int bj = 0; bj < 2; ++bj) *(u32x4*)(rowp + bj * HALF) = pack8(acc[ai][bj][m][0] * rs, acc[ai][bj][m][1] * rs); }
.LBB0_463:
	v_lshl_add_u32 v150, s95, 8, v152
	v_ashrrev_i32_e32 v151, 31, v150
	v_lshl_add_u64 v[146:147], v[150:151], 4, s[52:53]
	global_load_dwordx4 v[168:171], v[146:147], off
	global_load_dwordx4 v[172:175], v[146:147], off offset:256
	global_load_dwordx4 v[176:179], v[146:147], off offset:512
	global_load_dwordx4 v[180:183], v[146:147], off offset:768
	global_load_dwordx4 v[184:187], v[146:147], off offset:2048
	global_load_dwordx4 v[188:191], v[146:147], off offset:2304
	global_load_dwordx4 v[192:195], v[146:147], off offset:2560
	global_load_dwordx4 v[196:199], v[146:147], off offset:2816
	v_lshlrev_b64 v[148:149], 11, v[150:151]
	s_cmp_lt_i32 s96, 4
	s_cselect_b32 s1, s23, s7
	s_cselect_b32 s0, s22, s6
	s_lshl_b32 s16, s96, 9
	s_and_b32 s16, s16, 0x600
	s_add_u32 s0, s0, s16
	s_addc_u32 s1, s1, 0
	v_or_b32_e32 v162, 16, v150
	v_ashrrev_i32_e32 v163, 31, v162
	v_lshl_add_u64 v[164:165], v[162:163], 4, s[52:53]
	s_mov_b32 s16, 0x40000
	s_waitcnt vmcnt(0)
	v_mov_b32_e32 v158, v168
	v_mov_b32_e32 v159, v169
	v_mov_b32_e32 v160, v170
	v_mov_b32_e32 v161, v171
	v_mov_b32_e32 v166, v159
	v_mov_b32_e32 v167, v160
	v_mov_b32_e32 v159, v161
	v_pk_add_f32 v[158:159], v[166:167], v[158:159]
	v_lshl_add_u64 v[160:161], s[0:1], 0, v[136:137]
	v_add_f32_e32 v151, v158, v159
	v_fmamk_f32 v151, v151, 0x3b800000, v157
	v_rsq_f32_e32 v158, v151
	v_lshl_add_u64 v[148:149], v[160:161], 0, v[148:149]
	s_mov_b64 s[0:1], 0x40000
	v_pk_mul_f32 v[122:123], v[122:123], v[158:159] op_sel_hi:[1,0]
	v_pk_mul_f32 v[120:121], v[120:121], v[158:159] op_sel_hi:[1,0]
	v_pk_mul_f32 v[126:127], v[126:127], v[158:159] op_sel_hi:[1,0]
	v_pk_mul_f32 v[124:125], v[124:125], v[158:159] op_sel_hi:[1,0]
	v_pk_mul_f32 v[118:119], v[118:119], v[158:159] op_sel_hi:[1,0]
	v_pk_mul_f32 v[116:117], v[116:117], v[158:159] op_sel_hi:[1,0]
	v_pk_mul_f32 v[166:167], v[114:115], v[158:159] op_sel_hi:[1,0]
	v_pk_mul_f32 v[158:159], v[112:113], v[158:159] op_sel_hi:[1,0]
	v_cvt_pk_bf16_f32 v112, v120, v121
	v_cvt_pk_bf16_f32 v113, v122, v123
	v_cvt_pk_bf16_f32 v114, v124, v125
	v_cvt_pk_bf16_f32 v115, v126, v127
	v_cvt_pk_bf16_f32 v116, v116, v117
	v_cvt_pk_bf16_f32 v117, v118, v119
	v_cvt_pk_bf16_f32 v118, v158, v159
	v_cvt_pk_bf16_f32 v119, v166, v167
	global_store_dwordx4 v[148:149], v[112:115], off
	global_store_dwordx4 v[148:149], v[116:119], off offset:256
	s_nop 1
	s_nop 0
	v_or_b32_e32 v116, 32, v150
	v_ashrrev_i32_e32 v117, 31, v116
	v_mov_b32_e32 v112, v172
	v_mov_b32_e32 v113, v173
	v_mov_b32_e32 v114, v174
	v_mov_b32_e32 v115, v175
	v_mov_b32_e32 v118, v113
	v_mov_b32_e32 v119, v114
	v_mov_b32_e32 v113, v115
	v_pk_add_f32 v[112:113], v[118:119], v[112:113]
	v_lshlrev_b64 v[114:115], 11, v[162:163]
	v_add_f32_e32 v112, v112, v113
	v_fmamk_f32 v112, v112, 0x3b800000, v157
	v_rsq_f32_e32 v112, v112
	v_lshl_add_u64 v[114:115], v[160:161], 0, v[114:115]
	v_lshl_add_u64 v[118:119], v[116:117], 4, s[52:53]
	v_pk_mul_f32 v[110:111], v[110:111], v[112:113] op_sel_hi:[1,0]
	v_pk_mul_f32 v[108:109], v[108:109], v[112:113] op_sel_hi:[1,0]
	v_pk_mul_f32 v[106:107], v[106:107], v[112:113] op_sel_hi:[1,0]
	v_pk_mul_f32 v[104:105], v[104:105], v[112:113] op_sel_hi:[1,0]
	v_pk_mul_f32 v[102:103], v[102:103], v[112:113] op_sel_hi:[1,0]
	v_pk_mul_f32 v[100:101], v[100:101], v[112:113] op_sel_hi:[1,0]
	v_pk_mul_f32 v[120:121], v[98:99], v[112:113] op_sel_hi:[1,0]
	v_pk_mul_f32 v[112:113], v[96:97], v[112:113] op_sel_hi:[1,0]
	v_cvt_pk_bf16_f32 v96, v108, v109
	v_cvt_pk_bf16_f32 v97, v110, v111
	v_cvt_pk_bf16_f32 v98, v104, v105
	v_cvt_pk_bf16_f32 v99, v106, v107
	v_cvt_pk_bf16_f32 v100, v100, v101
	v_cvt_pk_bf16_f32 v101, v102, v103
	v_cvt_pk_bf16_f32 v102, v112, v113
	v_cvt_pk_bf16_f32 v103, v120, v121
	global_store_dwordx4 v[114:115], v[96:99], off
	global_store_dwordx4 v[114:115], v[100:103], off offset:256
	s_nop 1
	s_nop 0
	v_or_b32_e32 v100, 48, v150
	v_ashrrev_i32_e32 v101, 31, v100
	v_mov_b32_e32 v96, v176
	v_mov_b32_e32 v97, v177
	v_mov_b32_e32 v98, v178
	v_mov_b32_e32 v99, v179
	v_mov_b32_e32 v102, v97
	v_mov_b32_e32 v103, v98
	v_mov_b32_e32 v97, v99
	v_pk_add_f32 v[96:97], v[102:103], v[96:97]
	v_lshlrev_b64 v[98:99], 11, v[116:117]
	v_add_f32_e32 v96, v96, v97
	v_fmamk_f32 v96, v96, 0x3b800000, v157
	v_rsq_f32_e32 v96, v96
	v_lshl_add_u64 v[98:99], v[160:161], 0, v[98:99]
	v_lshl_add_u64 v[102:103], v[100:101], 4, s[52:53]
	v_pk_mul_f32 v[94:95], v[94:95], v[96:97] op_sel_hi:[1,0]
	v_pk_mul_f32 v[92:93], v[92:93], v[96:97] op_sel_hi:[1,0]
	v_pk_mul_f32 v[90:91], v[90:91], v[96:97] op_sel_hi:[1,0]
	v_pk_mul_f32 v[88:89], v[88:89], v[96:97] op_sel_hi:[1,0]
	v_pk_mul_f32 v[86:87], v[86:87], v[96:97] op_sel_hi:[1,0]
	v_pk_mul_f32 v[84:85], v[84:85], v[96:97] op_sel_hi:[1,0]
	v_pk_mul_f32 v[104:105], v[82:83], v[96:97] op_sel_hi:[1,0]
	v_pk_mul_f32 v[96:97], v[80:81], v[96:97] op_sel_hi:[1,0]
	v_cvt_pk_bf16_f32 v80, v92, v93
	v_cvt_pk_bf16_f32 v81, v94, v95
	v_cvt_pk_bf16_f32 v82, v88, v89
	v_cvt_pk_bf16_f32 v83, v90, v91
	v_cvt_pk_bf16_f32 v84, v84, v85
	v_cvt_pk_bf16_f32 v85, v86, v87
	v_cvt_pk_bf16_f32 v86, v96, v97
	v_cvt_pk_bf16_f32 v87, v104, v105
	global_store_dwordx4 v[98:99], v[80:83], off
	global_store_dwordx4 v[98:99], v[84:87], off offset:256
	s_nop 1
	v_mov_b32_e32 v80, v180
	v_mov_b32_e32 v81, v181
	v_mov_b32_e32 v82, v182
	v_mov_b32_e32 v83, v183
	v_mov_b32_e32 v84, v81
	v_mov_b32_e32 v85, v82
	v_mov_b32_e32 v81, v83
	v_pk_add_f32 v[80:81], v[84:85], v[80:81]
	v_lshlrev_b64 v[82:83], 11, v[100:101]
	v_add_f32_e32 v80, v80, v81
	v_fmamk_f32 v80, v80, 0x3b800000, v157
	v_rsq_f32_e32 v80, v80
	v_lshl_add_u64 v[82:83], v[160:161], 0, v[82:83]
; __device__ __forceinline__ u32x4 pack8(const f32x4 a, const f32x4 b) { u32x4 w; w.x = cvt_pk_bf16(a[0], a[1]); w.y = cvt_pk_bf16(a[2], a[3]); w.z = cvt_pk_bf16(b[0], b[1]); w.w = cvt_pk_bf16(b[2], b[3]); return w; }
; #define EPI_ROWLOOP _Pragma("unroll") for (int ai = 0; ai < 2; ++ai) _Pragma("unroll") for (int m = 0; m < 4; ++m)
;     __device__ __forceinline__ void operator()(const f32x4 (&acc)[2][2][4][2], const Unit& u, int wr, int wc, int fr, int fq) const {
;     ...
;         EPI_ROWLOOP { const int r = row0 + ai * HALF + m * 16; const f32x4 pq = part[r]; const float rs = __builtin_amdgcn_rsqf(((pq[0] + pq[1]) + (pq[2] + pq[3])) * (1.0f / 256.0f) + EP_EPS);
;             bf16_t* rowp = base + (size_t)r * 1024 + (pn & 3) * 256 + cl;
; #pragma unroll
;             for (int bj = 0; bj < 2; ++bj) *(u32x4*)(rowp + bj * HALF) = pack8(acc[ai][bj][m][0] * rs, acc[ai][bj][m][1] * rs); }
	v_pk_mul_f32 v[78:79], v[78:79], v[80:81] op_sel_hi:[1,0]
	v_pk_mul_f32 v[76:77], v[76:77], v[80:81] op_sel_hi:[1,0]
	v_pk_mul_f32 v[74:75], v[74:75], v[80:81] op_sel_hi:[1,0]
	v_pk_mul_f32 v[72:73], v[72:73], v[80:81] op_sel_hi:[1,0]
	v_pk_mul_f32 v[70:71], v[70:71], v[80:81] op_sel_hi:[1,0]
	v_pk_mul_f32 v[68:69], v[68:69], v[80:81] op_sel_hi:[1,0]
	v_pk_mul_f32 v[84:85], v[66:67], v[80:81] op_sel_hi:[1,0]
	v_pk_mul_f32 v[80:81], v[64:65], v[80:81] op_sel_hi:[1,0]
	v_cvt_pk_bf16_f32 v64, v76, v77
	v_cvt_pk_bf16_f32 v65, v78, v79
	v_cvt_pk_bf16_f32 v66, v72, v73
	v_cvt_pk_bf16_f32 v67, v74, v75
	v_cvt_pk_bf16_f32 v68, v68, v69
	v_cvt_pk_bf16_f32 v69, v70, v71
	v_cvt_pk_bf16_f32 v70, v80, v81
	v_cvt_pk_bf16_f32 v71, v84, v85
	global_store_dwordx4 v[82:83], v[64:67], off
	global_store_dwordx4 v[82:83], v[68:71], off offset:256
	s_nop 1
	s_nop 0
	v_lshl_add_u64 v[68:69], v[148:149], 0, s[0:1]
	s_mov_b64 s[0:1], 0x48000
	v_mov_b32_e32 v64, v184
	v_mov_b32_e32 v65, v185
	v_mov_b32_e32 v66, v186
	v_mov_b32_e32 v67, v187
	v_mov_b32_e32 v70, v65
	v_mov_b32_e32 v71, v66
	v_mov_b32_e32 v65, v67
	v_pk_add_f32 v[64:65], v[70:71], v[64:65]
	v_add_co_u32_e32 v66, vcc, s16, v148
	v_add_f32_e32 v64, v64, v65
	v_fmamk_f32 v64, v64, 0x3b800000, v157
	v_rsq_f32_e32 v64, v64
	v_addc_co_u32_e32 v67, vcc, 0, v149, vcc
	v_pk_mul_f32 v[62:63], v[62:63], v[64:65] op_sel_hi:[1,0]
	v_pk_mul_f32 v[60:61], v[60:61], v[64:65] op_sel_hi:[1,0]
	v_pk_mul_f32 v[58:59], v[58:59], v[64:65] op_sel_hi:[1,0]
	v_pk_mul_f32 v[56:57], v[56:57], v[64:65] op_sel_hi:[1,0]
	v_pk_mul_f32 v[54:55], v[54:55], v[64:65] op_sel_hi:[1,0]
	v_pk_mul_f32 v[52:53], v[52:53], v[64:65] op_sel_hi:[1,0]
	v_pk_mul_f32 v[70:71], v[50:51], v[64:65] op_sel_hi:[1,0]
	v_pk_mul_f32 v[64:65], v[48:49], v[64:65] op_sel_hi:[1,0]
	v_cvt_pk_bf16_f32 v48, v60, v61
	v_cvt_pk_bf16_f32 v49, v62, v63
	v_cvt_pk_bf16_f32 v50, v56, v57
	v_cvt_pk_bf16_f32 v51, v58, v59
	v_cvt_pk_bf16_f32 v52, v52, v53
	v_cvt_pk_bf16_f32 v53, v54, v55
	v_cvt_pk_bf16_f32 v54, v64, v65
	v_cvt_pk_bf16_f32 v55, v70, v71
	global_store_dwordx4 v[66:67], v[48:51], off
	global_store_dwordx4 v[68:69], v[52:55], off offset:256
	s_nop 1
	s_nop 0
	v_lshl_add_u64 v[52:53], v[148:149], 0, s[0:1]
	v_mov_b32_e32 v48, v188
	v_mov_b32_e32 v49, v189
	v_mov_b32_e32 v50, v190
	v_mov_b32_e32 v51, v191
	v_mov_b32_e32 v54, v49
	v_mov_b32_e32 v55, v50
	v_mov_b32_e32 v49, v51
	v_pk_add_f32 v[48:49], v[54:55], v[48:49]
	v_add_co_u32_e32 v50, vcc, s85, v148
	v_add_f32_e32 v48, v48, v49
	v_fmamk_f32 v48, v48, 0x3b800000, v157
	v_rsq_f32_e32 v48, v48
	v_addc_co_u32_e32 v51, vcc, 0, v149, vcc
	v_pk_mul_f32 v[46:47], v[46:47], v[48:49] op_sel_hi:[1,0]
	v_pk_mul_f32 v[44:45], v[44:45], v[48:49] op_sel_hi:[1,0]
	v_pk_mul_f32 v[42:43], v[42:43], v[48:49] op_sel_hi:[1,0]
	v_pk_mul_f32 v[40:41], v[40:41], v[48:49] op_sel_hi:[1,0]
	v_pk_mul_f32 v[38:39], v[38:39], v[48:49] op_sel_hi:[1,0]
	v_pk_mul_f32 v[36:37], v[36:37], v[48:49] op_sel_hi:[1,0]
	v_pk_mul_f32 v[54:55], v[34:35], v[48:49] op_sel_hi:[1,0]
	v_pk_mul_f32 v[48:49], v[32:33], v[48:49] op_sel_hi:[1,0]
	v_cvt_pk_bf16_f32 v32, v44, v45
	v_cvt_pk_bf16_f32 v33, v46, v47
	v_cvt_pk_bf16_f32 v34, v40, v41
	v_cvt_pk_bf16_f32 v35, v42, v43
	v_cvt_pk_bf16_f32 v36, v36, v37
	v_cvt_pk_bf16_f32 v37, v38, v39
	v_cvt_pk_bf16_f32 v38, v48, v49
	v_cvt_pk_bf16_f32 v39, v54, v55
	global_store_dwordx4 v[50:51], v[32:35], off
	global_store_dwordx4 v[52:53], v[36:39], off offset:256
	s_nop 1
	s_nop 0
	v_lshl_add_u64 v[36:37], v[148:149], 0, s[46:47]
	v_mov_b32_e32 v32, v192
	v_mov_b32_e32 v33, v193
	v_mov_b32_e32 v34, v194
	v_mov_b32_e32 v35, v195
	v_mov_b32_e32 v38, v33
	v_mov_b32_e32 v39, v34
	v_mov_b32_e32 v33, v35
	v_pk_add_f32 v[32:33], v[38:39], v[32:33]
	v_add_co_u32_e32 v34, vcc, s86, v148
	v_add_f32_e32 v32, v32, v33
	v_fmamk_f32 v32, v32, 0x3b800000, v157
	v_rsq_f32_e32 v32, v32
	v_addc_co_u32_e32 v35, vcc, 0, v149, vcc
	s_and_b64 vcc, exec, s[4:5]
	v_pk_mul_f32 v[30:31], v[30:31], v[32:33] op_sel_hi:[1,0]
	v_pk_mul_f32 v[28:29], v[28:29], v[32:33] op_sel_hi:[1,0]
	v_pk_mul_f32 v[26:27], v[26:27], v[32:33] op_sel_hi:[1,0]
	v_pk_mul_f32 v[24:25], v[24:25], v[32:33] op_sel_hi:[1,0]
	v_pk_mul_f32 v[22:23], v[22:23], v[32:33] op_sel_hi:[1,0]
	v_pk_mul_f32 v[20:21], v[20:21], v[32:33] op_sel_hi:[1,0]
	v_pk_mul_f32 v[38:39], v[18:19], v[32:33] op_sel_hi:[1,0]
	v_pk_mul_f32 v[32:33], v[16:17], v[32:33] op_sel_hi:[1,0]
	v_cvt_pk_bf16_f32 v16, v28, v29
	v_cvt_pk_bf16_f32 v17, v30, v31
	v_cvt_pk_bf16_f32 v18, v24, v25
	v_cvt_pk_bf16_f32 v19, v26, v27
	v_cvt_pk_bf16_f32 v20, v20, v21
	v_cvt_pk_bf16_f32 v21, v22, v23
	v_cvt_pk_bf16_f32 v22, v32, v33
	v_cvt_pk_bf16_f32 v23, v38, v39
	global_store_dwordx4 v[34:35], v[16:19], off
	global_store_dwordx4 v[36:37], v[20:23], off offset:256
	s_nop 1
	s_nop 0
	v_lshl_add_u64 v[20:21], v[148:149], 0, s[54:55]
	v_mov_b32_e32 v16, v196
	v_mov_b32_e32 v17, v197
	v_mov_b32_e32 v18, v198
	v_mov_b32_e32 v19, v199
	v_mov_b32_e32 v22, v17
	v_mov_b32_e32 v23, v18
	v_mov_b32_e32 v17, v19
	v_pk_add_f32 v[16:17], v[22:23], v[16:17]
	v_add_co_u32_e64 v18, s[0:1], s92, v148
	v_add_f32_e32 v16, v16, v17
	v_fmamk_f32 v16, v16, 0x3b800000, v157
	v_rsq_f32_e32 v16, v16
	v_addc_co_u32_e64 v19, s[0:1], 0, v149, s[0:1]
	s_mov_b64 s[0:1], -1
	v_pk_mul_f32 v[14:15], v[14:15], v[16:17] op_sel_hi:[1,0]
	v_pk_mul_f32 v[12:13], v[12:13], v[16:17] op_sel_hi:[1,0]
	v_pk_mul_f32 v[10:11], v[10:11], v[16:17] op_sel_hi:[1,0]
	v_pk_mul_f32 v[8:9], v[8:9], v[16:17] op_sel_hi:[1,0]
	v_pk_mul_f32 v[6:7], v[6:7], v[16:17] op_sel_hi:[1,0]
	v_pk_mul_f32 v[4:5], v[4:5], v[16:17] op_sel_hi:[1,0]
	v_pk_mul_f32 v[22:23], v[2:3], v[16:17] op_sel_hi:[1,0]
	v_pk_mul_f32 v[16:17], v[0:1], v[16:17] op_sel_hi:[1,0]
	v_cvt_pk_bf16_f32 v0, v12, v13
	v_cvt_pk_bf16_f32 v1, v14, v15
	v_cvt_pk_bf16_f32 v2, v8, v9
	v_cvt_pk_bf16_f32 v3, v10, v11
	v_cvt_pk_bf16_f32 v4, v4, v5
	v_cvt_pk_bf16_f32 v5, v6, v7
	v_cvt_pk_bf16_f32 v6, v16, v17
	v_cvt_pk_bf16_f32 v7, v22, v23
	global_store_dwordx4 v[18:19], v[0:3], off
	global_store_dwordx4 v[20:21], v[4:7], off offset:256
	s_cbranch_vccnz .LBB0_451
	s_andn2_b64 vcc, exec, s[12:13]
	s_cbranch_vccnz .LBB0_450
	s_barrier
	s_branch .LBB0_450
